# GLA step f: LDS operand reads of the o+=S.q chain issued ahead through a 5-buffer ring
# baseline (speedup 1.0000x reference)
; #define LAS __attribute__((address_space(3)))
; DI unsigned cvt_pk_bf16(float lo, float hi) { const f32x2_t v = {lo, hi}; const bf16v2_t b = __builtin_convertvector(v, bf16v2_t); return __builtin_bit_cast(unsigned, b); }
; DI f32x4 mfma16(bf16x8 a, bf16x8 b, f32x4 c) { return __builtin_amdgcn_mfma_f32_16x16x32_bf16(a, b, c, 0, 0, 0); }
; DI void gla_item(ldsp lds, const Params& p, const bf16_t* proj, bf16_t* obuf, const float* q0k0, int jl, int item, int tid, int wid, int lane) {
;     ...
;         if (wid < 6) {
;             const int e0 = 16 * wid;
;             bf16x8 vf[2];
; #pragma unroll
;             for (int ks = 0; ks < 2; ++ks) { const ldsp a0 = Vl + (32 * ks + quad * 8 + (li >> 2)) * S96 + (e0 + 4 * (li & 3)) * 2; vf[ks] = lds_tr8(a0, a0 + 4 * S96); }
;             f32x4 o[4];
; #pragma unroll
;             for (int ti = 0; ti < 4; ++ti) { o[ti] = (f32x4){0.f, 0.f, 0.f, 0.f};
; #pragma unroll
;                 for (int ks = 0; ks < 2; ++ks) if (2 * ks <= ti) o[ti] = mfma16(vf[ks], lds_rd8(AM + (16 * ti + li) * SAM + (32 * ks + quad * 8) * 2), o[ti]); }
; #pragma unroll
;             for (int ks = 0; ks < 3; ++ks) { const bf16x8 a = lds_rd8(ST + (e0 + li) * S96 + (32 * ks + quad * 8) * 2);
; #pragma unroll
;                 for (int ti = 0; ti < 4; ++ti) o[ti] = mfma16(a, lds_rd8(QI + (16 * ti + li) * S96 + (32 * ks + quad * 8) * 2), o[ti]); }
; #pragma unroll
;             for (int ti = 0; ti < 4; ++ti) { u32x2 w; w.x = cvt_pk_bf16(o[ti][0], o[ti][1]); w.y = cvt_pk_bf16(o[ti][2], o[ti][3]);
;                 *(u32x2*)(obuf + (rowb + 16 * ti + li) * 768 + h * 192 + half * 96 + e0 + quad * 4) = w; }
; #pragma unroll
;             for (int dt = 0; dt < 6; ++dt) {
;                 const f32x4 lb = *(LAS f32x4*)(LA + 63 * SLA + 16 * dt + quad * 4);
; #pragma unroll
;                 for (int jj = 0; jj < 4; ++jj) S[dt][jj] *= __expf(lb[jj]);
.LBB0_502:
	s_and_b64 vcc, exec, s[74:75]
	ds_write_b64 v190, v[14:15]
	s_waitcnt lgkmcnt(0)
	s_barrier
	s_cbranch_vccnz .LBB0_483
	ds_read_b64_tr_b16 v[64:65], v191
	ds_read_b64_tr_b16 v[66:67], v191 offset:832
	ds_read_b64_tr_b16 v[60:61], v191 offset:6656
	ds_read_b64_tr_b16 v[62:63], v191 offset:7488
	ds_read_b128 v[200:203], v192
	ds_read_b128 v[204:207], v192 offset:2304
	ds_read_b128 v[208:211], v192 offset:4608
	ds_read_b128 v[212:215], v192 offset:4672
	ds_read_b128 v[216:219], v193 offset:64
	s_waitcnt lgkmcnt(2)
	v_mfma_f32_16x16x32_bf16 v[208:211], v[64:67], v[208:211], 0
	v_add_u32_e32 v13, v165, v69
	v_lshl_add_u64 v[158:159], v[142:143], 0, v[140:141]
	s_mov_b32 s14, 0x26846000
	s_waitcnt lgkmcnt(1)
	v_mfma_f32_16x16x32_bf16 v[208:211], v[60:63], v[212:215], v[208:211]
	ds_read_b128 v[212:215], v193
	s_waitcnt lgkmcnt(0)
	v_mfma_f32_16x16x32_bf16 v[212:215], v[64:67], v[212:215], 0
	v_mfma_f32_16x16x32_bf16 v[212:215], v[60:63], v[216:219], v[212:215]
	ds_read_b128 v[216:219], v13
	ds_read_b128 v[220:223], v194 offset:38912
	ds_read_b128 v[224:227], v194 offset:42240
	ds_read_b128 v[242:245], v194 offset:45568
	ds_read_b128 v[246:249], v195 offset:38912
	v_mfma_f32_16x16x32_bf16 v[200:203], v[64:67], v[200:203], 0
	v_mfma_f32_16x16x32_bf16 v[204:207], v[64:67], v[204:207], 0
	s_waitcnt lgkmcnt(3)
	v_mfma_f32_16x16x32_bf16 v[200:203], v[216:219], v[220:223], v[200:203]
	ds_read_b128 v[220:223], v13 offset:64
	s_waitcnt lgkmcnt(3)
	v_mfma_f32_16x16x32_bf16 v[204:207], v[216:219], v[224:227], v[204:207]
	ds_read_b128 v[224:227], v194 offset:38976
	s_waitcnt lgkmcnt(3)
	v_mfma_f32_16x16x32_bf16 v[208:211], v[216:219], v[242:245], v[208:211]
	ds_read_b128 v[242:245], v194 offset:42304
	s_waitcnt lgkmcnt(3)
	v_mfma_f32_16x16x32_bf16 v[212:215], v[216:219], v[246:249], v[212:215]
	ds_read_b128 v[246:249], v194 offset:45632
	ds_read_b128 v[216:219], v195 offset:38976
	s_waitcnt lgkmcnt(3)
	v_mfma_f32_16x16x32_bf16 v[200:203], v[220:223], v[224:227], v[200:203]
	ds_read_b128 v[224:227], v13 offset:128
	s_waitcnt lgkmcnt(3)
	v_mfma_f32_16x16x32_bf16 v[204:207], v[220:223], v[242:245], v[204:207]
	ds_read_b128 v[242:245], v194 offset:39040
	s_waitcnt lgkmcnt(3)
	v_mfma_f32_16x16x32_bf16 v[208:211], v[220:223], v[246:249], v[208:211]
	ds_read_b128 v[246:249], v194 offset:42368
	s_waitcnt lgkmcnt(3)
	v_mfma_f32_16x16x32_bf16 v[212:215], v[220:223], v[216:219], v[212:215]
	ds_read_b128 v[216:219], v194 offset:45696
	ds_read_b128 v[220:223], v195 offset:39040
	s_waitcnt lgkmcnt(3)
	v_mfma_f32_16x16x32_bf16 v[200:203], v[224:227], v[242:245], v[200:203]
	s_waitcnt lgkmcnt(2)
	v_mfma_f32_16x16x32_bf16 v[204:207], v[224:227], v[246:249], v[204:207]
	s_waitcnt lgkmcnt(1)
	v_mfma_f32_16x16x32_bf16 v[208:211], v[224:227], v[216:219], v[208:211]
	s_waitcnt lgkmcnt(0)
	v_mfma_f32_16x16x32_bf16 v[212:215], v[224:227], v[220:223], v[212:215]
	s_nop 1
	v_cvt_pk_bf16_f32 v14, v200, v201
	v_cvt_pk_bf16_f32 v15, v202, v203
	ds_read_b128 v[200:203], v89 offset:38512
	global_store_dwordx2 v[158:159], v[14:15], off
	v_lshl_add_u64 v[158:159], s[6:7], 0, v[138:139]
	v_add_co_u32_e32 v160, vcc, s14, v158
	v_cvt_pk_bf16_f32 v14, v204, v205
	v_cvt_pk_bf16_f32 v15, v206, v207
	v_addc_co_u32_e32 v161, vcc, 0, v159, vcc
	s_mov_b32 s14, 0x2684c000
	global_store_dwordx2 v[160:161], v[14:15], off
	v_add_co_u32_e32 v160, vcc, s14, v158
	s_mov_b32 s14, 0x26852000
	s_nop 0
	v_addc_co_u32_e32 v161, vcc, 0, v159, vcc
	v_cvt_pk_bf16_f32 v14, v208, v209
	v_cvt_pk_bf16_f32 v15, v210, v211
	v_add_co_u32_e32 v158, vcc, s14, v158
	global_store_dwordx2 v[160:161], v[14:15], off
	v_cvt_pk_bf16_f32 v14, v212, v213
	v_cvt_pk_bf16_f32 v15, v214, v215
	v_addc_co_u32_e32 v159, vcc, 0, v159, vcc
	s_waitcnt lgkmcnt(0)
	v_mul_f32_e32 v13, 0x3fb8aa3b, v200
	global_store_dwordx2 v[158:159], v[14:15], off
	v_exp_f32_e32 v14, v13
	v_mul_f32_e32 v13, 0x3fb8aa3b, v201
	v_exp_f32_e32 v15, v13
	v_mul_f32_e32 v13, 0x3fb8aa3b, v202
	v_exp_f32_e32 v158, v13
	v_mul_f32_e32 v13, 0x3fb8aa3b, v203
	v_exp_f32_e32 v159, v13
	ds_read_b64_tr_b16 v[202:203], v196 offset:832
	ds_read_b64_tr_b16 v[200:201], v196
	ds_read_b64_tr_b16 v[204:205], v196 offset:32
	v_pk_mul_f32 v[40:41], v[40:41], v[14:15]
	v_pk_mul_f32 v[42:43], v[42:43], v[158:159]
	s_waitcnt lgkmcnt(1)
; #define LAS __attribute__((address_space(3)))
; DI f32x4 mfma16(bf16x8 a, bf16x8 b, f32x4 c) { return __builtin_amdgcn_mfma_f32_16x16x32_bf16(a, b, c, 0, 0, 0); }
; DI void gla_item(ldsp lds, const Params& p, const bf16_t* proj, bf16_t* obuf, const float* q0k0, int jl, int item, int tid, int wid, int lane) {
;     ...
;             for (int dt = 0; dt < 6; ++dt) {
;                 const f32x4 lb = *(LAS f32x4*)(LA + 63 * SLA + 16 * dt + quad * 4);
; #pragma unroll
;                 for (int jj = 0; jj < 4; ++jj) S[dt][jj] *= __expf(lb[jj]);
; #pragma unroll
;                 for (int ks = 0; ks < 2; ++ks) { const ldsp a0 = KO + (32 * ks + quad * 8 + (li >> 2)) * S96 + (16 * dt + 4 * (li & 3)) * 2; S[dt] = mfma16(lds_tr8(a0, a0 + 4 * S96), vf[ks], S[dt]); }
;             }
	s_nop 0
	v_mfma_f32_16x16x32_bf16 v[40:43], v[200:203], v[64:67], v[40:43]
	ds_read_b64_tr_b16 v[200:201], v196 offset:6656
	ds_read_b64_tr_b16 v[202:203], v196 offset:7488
	ds_read_b64_tr_b16 v[206:207], v196 offset:864
	s_waitcnt lgkmcnt(1)
	v_mfma_f32_16x16x32_bf16 v[40:43], v[200:203], v[60:63], v[40:43]
	ds_read_b128 v[200:203], v89 offset:38576
	s_waitcnt lgkmcnt(0)
	v_mul_f32_e32 v13, 0x3fb8aa3b, v200
	v_exp_f32_e32 v14, v13
	v_mul_f32_e32 v13, 0x3fb8aa3b, v201
	v_exp_f32_e32 v15, v13
	v_mul_f32_e32 v13, 0x3fb8aa3b, v202
	v_exp_f32_e32 v158, v13
	v_mul_f32_e32 v13, 0x3fb8aa3b, v203
	v_exp_f32_e32 v159, v13
	v_pk_mul_f32 v[52:53], v[52:53], v[14:15]
	ds_read_b64_tr_b16 v[200:201], v196 offset:6688
	ds_read_b64_tr_b16 v[202:203], v196 offset:7520
	v_pk_mul_f32 v[54:55], v[54:55], v[158:159]
	s_nop 1
	v_mfma_f32_16x16x32_bf16 v[52:55], v[204:207], v[64:67], v[52:55]
	s_waitcnt lgkmcnt(0)
	v_mfma_f32_16x16x32_bf16 v[52:55], v[200:203], v[60:63], v[52:55]
	ds_read_b128 v[200:203], v89 offset:38640
	s_waitcnt lgkmcnt(0)
	v_mul_f32_e32 v13, 0x3fb8aa3b, v200
	v_exp_f32_e32 v14, v13
	v_mul_f32_e32 v13, 0x3fb8aa3b, v201
	v_exp_f32_e32 v15, v13
	v_mul_f32_e32 v13, 0x3fb8aa3b, v202
	v_exp_f32_e32 v158, v13
	v_mul_f32_e32 v13, 0x3fb8aa3b, v203
	v_exp_f32_e32 v159, v13
	ds_read_b64_tr_b16 v[200:201], v196 offset:64
	ds_read_b64_tr_b16 v[202:203], v196 offset:896
	v_pk_mul_f32 v[48:49], v[48:49], v[14:15]
	v_pk_mul_f32 v[50:51], v[50:51], v[158:159]
	s_waitcnt lgkmcnt(0)
	s_nop 0
	v_mfma_f32_16x16x32_bf16 v[48:51], v[200:203], v[64:67], v[48:51]
	ds_read_b64_tr_b16 v[200:201], v196 offset:6720
	ds_read_b64_tr_b16 v[202:203], v196 offset:7552
	s_waitcnt lgkmcnt(0)
	v_mfma_f32_16x16x32_bf16 v[48:51], v[200:203], v[60:63], v[48:51]
	ds_read_b128 v[200:203], v89 offset:38704
	s_waitcnt lgkmcnt(0)
	v_mul_f32_e32 v13, 0x3fb8aa3b, v200
	v_exp_f32_e32 v14, v13
	v_mul_f32_e32 v13, 0x3fb8aa3b, v201
	v_exp_f32_e32 v15, v13
	v_mul_f32_e32 v13, 0x3fb8aa3b, v202
	v_exp_f32_e32 v158, v13
	v_mul_f32_e32 v13, 0x3fb8aa3b, v203
	v_exp_f32_e32 v159, v13
	ds_read_b64_tr_b16 v[200:201], v196 offset:96
	ds_read_b64_tr_b16 v[202:203], v196 offset:928
	v_pk_mul_f32 v[36:37], v[36:37], v[14:15]
	v_pk_mul_f32 v[38:39], v[38:39], v[158:159]
	s_waitcnt lgkmcnt(0)
	s_nop 0
	v_mfma_f32_16x16x32_bf16 v[36:39], v[200:203], v[64:67], v[36:39]
	ds_read_b64_tr_b16 v[200:201], v196 offset:6752
	ds_read_b64_tr_b16 v[202:203], v196 offset:7584
	s_waitcnt lgkmcnt(0)
	v_mfma_f32_16x16x32_bf16 v[36:39], v[200:203], v[60:63], v[36:39]
	ds_read_b128 v[200:203], v89 offset:38768
	s_waitcnt lgkmcnt(0)
	v_mul_f32_e32 v13, 0x3fb8aa3b, v200
	v_exp_f32_e32 v14, v13
	v_mul_f32_e32 v13, 0x3fb8aa3b, v201
	v_exp_f32_e32 v15, v13
	v_mul_f32_e32 v13, 0x3fb8aa3b, v202
	v_exp_f32_e32 v158, v13
	v_mul_f32_e32 v13, 0x3fb8aa3b, v203
	v_exp_f32_e32 v159, v13
	ds_read_b64_tr_b16 v[200:201], v196 offset:128
	ds_read_b64_tr_b16 v[202:203], v196 offset:960
	v_pk_mul_f32 v[44:45], v[44:45], v[14:15]
	v_pk_mul_f32 v[46:47], v[46:47], v[158:159]
	s_waitcnt lgkmcnt(0)
	s_nop 0
	v_mfma_f32_16x16x32_bf16 v[44:47], v[200:203], v[64:67], v[44:47]
	ds_read_b64_tr_b16 v[200:201], v196 offset:6784
	ds_read_b64_tr_b16 v[202:203], v196 offset:7616
	s_waitcnt lgkmcnt(0)
	v_mfma_f32_16x16x32_bf16 v[44:47], v[200:203], v[60:63], v[44:47]
	ds_read_b128 v[200:203], v89 offset:38832
	s_waitcnt lgkmcnt(0)
	v_mul_f32_e32 v13, 0x3fb8aa3b, v200
	v_exp_f32_e32 v14, v13
	v_mul_f32_e32 v13, 0x3fb8aa3b, v201
	v_exp_f32_e32 v15, v13
	v_mul_f32_e32 v13, 0x3fb8aa3b, v202
	v_exp_f32_e32 v158, v13
	v_mul_f32_e32 v13, 0x3fb8aa3b, v203
	v_exp_f32_e32 v159, v13
	ds_read_b64_tr_b16 v[200:201], v196 offset:160
	ds_read_b64_tr_b16 v[202:203], v196 offset:992
	v_pk_mul_f32 v[56:57], v[56:57], v[14:15]
	v_pk_mul_f32 v[58:59], v[58:59], v[158:159]
	s_waitcnt lgkmcnt(0)
	s_nop 0
	v_mfma_f32_16x16x32_bf16 v[56:59], v[200:203], v[64:67], v[56:59]
	ds_read_b64_tr_b16 v[64:65], v196 offset:6816
	ds_read_b64_tr_b16 v[66:67], v196 offset:7648
	s_waitcnt lgkmcnt(0)
	v_mfma_f32_16x16x32_bf16 v[56:59], v[64:67], v[60:63], v[56:59]
	s_branch .LBB0_483
